# E2 sample spatial gate as an 8-wave workgroup task (wave = row), loads requested up front
# baseline (speedup 1.0000x reference)
; __device__ __forceinline__ float bf_lo(unsigned w) { return __uint_as_float(w << 16); }
; __device__ __forceinline__ float bf_hi(unsigned w) { return __uint_as_float(w & 0xffff0000u); }
; __device__ __forceinline__ void gate_sample_item(const bf16_t* z, bf16_t* mix, float* cvs  , const float* w_s, const float* b_s,
;                                                  const float* lnv_g, const float* lnv_b, int it, int lane) {
;     const int cq = it & 7, b = it >> 3, gr = cq >> 1;
;     const size_t tok0 = (size_t)T_P + b * 8;
;     const int c = cq * 128 + 2 * lane;
;     float vn0[8], vn1[8];
; #pragma unroll
;     for (int j = 0; j < 8; ++j) {
;         const bf16_t* vp = z + (tok0 + j) * EIN + 3328 + lane * 16;
;         const u32x4 a = *(const u32x4*)vp, cc = *(const u32x4*)(vp + 8);
;         float v[16] = {bf_lo(a.x), bf_hi(a.x), bf_lo(a.y), bf_hi(a.y), bf_lo(a.z), bf_hi(a.z), bf_lo(a.w), bf_hi(a.w),
;                        bf_lo(cc.x), bf_hi(cc.x), bf_lo(cc.y), bf_hi(cc.y), bf_lo(cc.z), bf_hi(cc.z), bf_lo(cc.w), bf_hi(cc.w)};
;         float s = 0.f;
; #pragma unroll
;         for (int e = 0; e < 16; ++e) s += v[e];
;         const float mean = wave_sum(s) * (1.0f / 1024.0f);
;         float q = 0.f;
; #pragma unroll
;         for (int e = 0; e < 16; ++e) { const float d = v[e] - mean; q += d * d; }
;         const float rstd = rsqrtf(wave_sum(q) * (1.0f / 1024.0f) + EPSN);
;         const unsigned xw = *(const unsigned*)(z + (tok0 + j) * EIN + 3328 + c);
;         vn0[j] = (bf_lo(xw) - mean) * rstd * lnv_g[c] + lnv_b[c];
;         vn1[j] = (bf_hi(xw) - mean) * rstd * lnv_g[c + 1] + lnv_b[c + 1];
;         *(f32x2*)(cvs + ((size_t)b * 8 + j) * 1024 + c) = (f32x2){vn0[j], vn1[j]};
;     ...
;         float m0 = b_s[gr * 128 + t], m1 = m0;
; #pragma unroll
;         for (int j = 0; j < 8; ++j)
;             if (j <= t) { const float w = w_s[((size_t)gr * 128 + t) * 128 + j]; m0 += w * vn0[j]; m1 += w * vn1[j]; }
;         const unsigned uw = *(const unsigned*)(z + (tok0 + t) * EIN + 2304 + c), gw = *(const unsigned*)(z + (tok0 + t) * EIN + 4352 + c);
.LBB0_1091:
	v_readlane_b32 s4, v254, 52
	v_readlane_b32 s5, v254, 53
	s_lshl_b64 s[4:5], s[4:5], 20
	v_readlane_b32 s6, v255, 1
	v_readlane_b32 s7, v255, 2
	s_add_u32 s4, s6, s4
	s_addc_u32 s5, s7, s5
	s_add_u32 s12, s4, 0x16280000
	v_readlane_b32 s4, v255, 0
	s_addc_u32 s13, s5, 0
	s_and_b32 s4, s4, 0x1c0
	v_lshlrev_b32_e32 v0, 4, v82
	s_cmpk_eq_i32 s4, 0x80
	s_cselect_b64 s[4:5], -1, 0
	v_lshlrev_b32_e32 v27, 1, v0
	s_cmpk_lg_i32 s88, 0x100
	s_cbranch_scc1 .LBB0_1093
	s_lshr_b32 s16, s54, 3
	s_and_b32 s17, s54, 7
	s_and_b32 s18, s16, 7
	s_lshr_b32 s19, s16, 3
	s_lshr_b32 s20, s18, 1
	v_readlane_b32 s22, v254, 42
	v_readlane_b32 s23, v254, 43
	v_readlane_b32 s24, v255, 7
	v_readlane_b32 s25, v255, 8
	s_lshl_b32 s21, s19, 3
	s_add_i32 s21, s21, s17
	s_mul_i32 s26, s21, 0x2a00
	s_add_u32 s26, s26, 0x5400000
	s_add_u32 s28, s22, 0x13e08000
	s_addc_u32 s29, s23, 0
	s_add_u32 s28, s28, s26
	s_addc_u32 s29, s29, 0
	s_add_u32 s30, s28, 0x1a00
	s_addc_u32 s31, s29, 0
	s_lshl_b32 s27, s18, 8
	s_add_u32 s34, s30, s27
	s_addc_u32 s35, s31, 0
	v_lshlrev_b32_e32 v0, 5, v215
	v_lshlrev_b32_e32 v28, 2, v215
	v_lshlrev_b32_e32 v29, 3, v215
	global_load_dwordx4 v[2:5], v0, s[30:31]
	global_load_dwordx4 v[6:9], v0, s[30:31] offset:16
	global_load_dword v10, v28, s[34:35]
	s_lshl_b32 s27, s18, 9
	s_add_u32 s36, s76, s27
	s_addc_u32 s37, s77, 0
	global_load_dwordx2 v[12:13], v29, s[36:37]
	s_add_u32 s38, s78, s27
	s_addc_u32 s39, s79, 0
	global_load_dwordx2 v[14:15], v29, s[38:39]
	global_load_dword v11, v28, s[34:35] offset:-2048
	global_load_dword v16, v28, s[34:35] offset:2048
	s_lshl_b32 s27, s20, 7
	s_add_i32 s27, s27, s17
	s_lshl_b32 s36, s27, 2
	s_add_u32 s24, s24, s36
	s_addc_u32 s25, s25, 0
	global_load_dword v17, v1, s[24:25]
	s_lshl_b32 s36, s27, 9
	s_add_u32 s36, s90, s36
	s_addc_u32 s37, s91, 0
	global_load_dwordx4 v[18:21], v1, s[36:37]
	global_load_dwordx4 v[22:25], v1, s[36:37] offset:16
	s_waitcnt vmcnt(8)
	v_lshlrev_b32_e32 v30, 16, v2
	v_and_b32_e32 v31, 0xffff0000, v2
	v_lshlrev_b32_e32 v32, 16, v3
	v_and_b32_e32 v33, 0xffff0000, v3
	v_lshlrev_b32_e32 v34, 16, v4
	v_and_b32_e32 v35, 0xffff0000, v4
	v_lshlrev_b32_e32 v36, 16, v5
	v_and_b32_e32 v37, 0xffff0000, v5
	v_lshlrev_b32_e32 v38, 16, v6
	v_and_b32_e32 v39, 0xffff0000, v6
	v_lshlrev_b32_e32 v40, 16, v7
	v_and_b32_e32 v41, 0xffff0000, v7
	v_lshlrev_b32_e32 v42, 16, v8
	v_and_b32_e32 v43, 0xffff0000, v8
	v_lshlrev_b32_e32 v44, 16, v9
	v_and_b32_e32 v45, 0xffff0000, v9
	v_add_f32_e32 v46, 0, v30
	v_add_f32_e32 v46, v46, v31
	v_add_f32_e32 v46, v46, v32
	v_add_f32_e32 v46, v46, v33
	v_add_f32_e32 v46, v46, v34
	v_add_f32_e32 v46, v46, v35
	v_add_f32_e32 v46, v46, v36
	v_add_f32_e32 v46, v46, v37
	v_add_f32_e32 v46, v46, v38
	v_add_f32_e32 v46, v46, v39
	v_add_f32_e32 v46, v46, v40
	v_add_f32_e32 v46, v46, v41
	v_add_f32_e32 v46, v46, v42
	v_add_f32_e32 v46, v46, v43
	v_add_f32_e32 v46, v46, v44
	v_add_f32_e32 v46, v46, v45
	s_waitcnt lgkmcnt(0)
	s_nop 1
	v_add_f32_dpp v46, v46, v46 quad_perm:[1,0,3,2] row_mask:0xf bank_mask:0xf
	s_nop 1
	v_add_f32_dpp v46, v46, v46 quad_perm:[2,3,0,1] row_mask:0xf bank_mask:0xf
	s_nop 1
	v_add_f32_dpp v46, v46, v46 row_half_mirror row_mask:0xf bank_mask:0xf
	s_nop 1
	v_add_f32_dpp v46, v46, v46 row_mirror row_mask:0xf bank_mask:0xf
	s_nop 1
	v_add_f32_dpp v46, v46, v46 row_bcast:15 row_mask:0xa bank_mask:0xf
	s_nop 1
	v_add_f32_dpp v46, v46, v46 row_bcast:31 row_mask:0xc bank_mask:0xf
	s_nop 1
	v_readlane_b32 s100, v46, 63
	s_nop 1
	v_mov_b32_e32 v46, s100
	v_fmac_f32_e32 v30, 0xba800000, v46
	v_fmac_f32_e32 v31, 0xba800000, v46
	v_fmac_f32_e32 v32, 0xba800000, v46
	v_fmac_f32_e32 v33, 0xba800000, v46
	v_fmac_f32_e32 v34, 0xba800000, v46
	v_fmac_f32_e32 v35, 0xba800000, v46
	v_fmac_f32_e32 v36, 0xba800000, v46
	v_fmac_f32_e32 v37, 0xba800000, v46
	v_fmac_f32_e32 v38, 0xba800000, v46
	v_fmac_f32_e32 v39, 0xba800000, v46
	v_fmac_f32_e32 v40, 0xba800000, v46
	v_fmac_f32_e32 v41, 0xba800000, v46
	v_fmac_f32_e32 v42, 0xba800000, v46
	v_fmac_f32_e32 v43, 0xba800000, v46
	v_fmac_f32_e32 v44, 0xba800000, v46
	v_fmac_f32_e32 v45, 0xba800000, v46
	v_mul_f32_e32 v47, v30, v30
	v_fmac_f32_e32 v47, v31, v31
	v_fmac_f32_e32 v47, v32, v32
	v_fmac_f32_e32 v47, v33, v33
	v_fmac_f32_e32 v47, v34, v34
	v_fmac_f32_e32 v47, v35, v35
	v_fmac_f32_e32 v47, v36, v36
	v_fmac_f32_e32 v47, v37, v37
	v_fmac_f32_e32 v47, v38, v38
	v_fmac_f32_e32 v47, v39, v39
	v_fmac_f32_e32 v47, v40, v40
	v_fmac_f32_e32 v47, v41, v41
	v_fmac_f32_e32 v47, v42, v42
	v_fmac_f32_e32 v47, v43, v43
	v_fmac_f32_e32 v47, v44, v44
	v_fmac_f32_e32 v47, v45, v45
	s_waitcnt lgkmcnt(0)
	s_nop 1
	v_add_f32_dpp v47, v47, v47 quad_perm:[1,0,3,2] row_mask:0xf bank_mask:0xf
	s_nop 1
	v_add_f32_dpp v47, v47, v47 quad_perm:[2,3,0,1] row_mask:0xf bank_mask:0xf
	s_nop 1
	v_add_f32_dpp v47, v47, v47 row_half_mirror row_mask:0xf bank_mask:0xf
	s_nop 1
	v_add_f32_dpp v47, v47, v47 row_mirror row_mask:0xf bank_mask:0xf
	s_nop 1
	v_add_f32_dpp v47, v47, v47 row_bcast:15 row_mask:0xa bank_mask:0xf
	s_nop 1
	v_add_f32_dpp v47, v47, v47 row_bcast:31 row_mask:0xc bank_mask:0xf
	s_nop 1
	v_readlane_b32 s100, v47, 63
	s_nop 1
	v_mov_b32_e32 v47, s100
	v_fmamk_f32 v47, v47, 0x3a800000, v138
	v_rsq_f32_e32 v47, v47
	v_mul_f32_e32 v48, 0x3a800000, v46
	s_waitcnt vmcnt(5)
	v_lshlrev_b32_e32 v30, 16, v10
	v_and_b32_e32 v31, 0xffff0000, v10
	v_sub_f32_e32 v30, v30, v48
	v_sub_f32_e32 v31, v31, v48
	v_mul_f32_e32 v30, v30, v47
	v_mul_f32_e32 v31, v31, v47
	v_pk_fma_f32 v[32:33], v[12:13], v[30:31], v[14:15]
	s_lshl_b32 s36, s21, 12
	s_lshl_b32 s27, s18, 9
	s_add_i32 s36, s36, s27
	s_add_u32 s36, s12, s36
	s_addc_u32 s37, s13, 0
	s_lshl_b32 s27, s17, 9
	v_add_u32_e32 v34, s27, v29
	v_add_u32_e32 v34, 0xa000, v34
	global_store_dwordx2 v29, v[32:33], s[36:37]
	ds_write_b64 v34, v[32:33]
	s_waitcnt lgkmcnt(0)
	s_barrier
; __device__ __forceinline__ float bf_lo(unsigned w) { return __uint_as_float(w << 16); }
; __device__ __forceinline__ float bf_hi(unsigned w) { return __uint_as_float(w & 0xffff0000u); }
; __device__ __forceinline__ unsigned pk2(float lo, float hi) { return pg8::cvt_pk_bf16(lo, hi); }
; __device__ __forceinline__ void gate_sample_item(const bf16_t* z, bf16_t* mix, float* cvs  , const float* w_s, const float* b_s,
;                                                  const float* lnv_g, const float* lnv_b, int it, int lane) {
;     ...
;     for (int t = 0; t < 8; ++t) {
;         float m0 = b_s[gr * 128 + t], m1 = m0;
; #pragma unroll
;         for (int j = 0; j < 8; ++j)
;             if (j <= t) { const float w = w_s[((size_t)gr * 128 + t) * 128 + j]; m0 += w * vn0[j]; m1 += w * vn1[j]; }
;         const unsigned uw = *(const unsigned*)(z + (tok0 + t) * EIN + 2304 + c), gw = *(const unsigned*)(z + (tok0 + t) * EIN + 4352 + c);
;         *(unsigned*)(mix + (tok0 + t) * 2048 + 1024 + c) = pk2(bf_lo(gw) * bf_lo(uw) * m0, bf_hi(gw) * bf_hi(uw) * m1);
;     }
	v_add_u32_e32 v49, 0xa000, v29
	ds_read_b64 v[30:31], v49 offset:0
	ds_read_b64 v[32:33], v49 offset:512
	ds_read_b64 v[34:35], v49 offset:1024
	ds_read_b64 v[36:37], v49 offset:1536
	ds_read_b64 v[38:39], v49 offset:2048
	ds_read_b64 v[40:41], v49 offset:2560
	ds_read_b64 v[42:43], v49 offset:3072
	ds_read_b64 v[44:45], v49 offset:3584
	s_waitcnt vmcnt(1)
	v_mov_b32_e32 v46, v17
	v_mov_b32_e32 v47, v17
	v_lshlrev_b32_e32 v2, 16, v11
	v_and_b32_e32 v3, 0xffff0000, v11
	v_lshlrev_b32_e32 v4, 16, v16
	v_and_b32_e32 v5, 0xffff0000, v16
	v_pk_mul_f32 v[2:3], v[4:5], v[2:3]
	s_waitcnt lgkmcnt(0)
	v_fmac_f32_e32 v46, v18, v30
	v_fmac_f32_e32 v47, v18, v31
	s_cmp_lt_u32 s17, 1
	s_cbranch_scc1 .Lsg_done
	v_fmac_f32_e32 v46, v19, v32
	v_fmac_f32_e32 v47, v19, v33
	s_cmp_lt_u32 s17, 2
	s_cbranch_scc1 .Lsg_done
	v_fmac_f32_e32 v46, v20, v34
	v_fmac_f32_e32 v47, v20, v35
	s_cmp_lt_u32 s17, 3
	s_cbranch_scc1 .Lsg_done
	v_fmac_f32_e32 v46, v21, v36
	v_fmac_f32_e32 v47, v21, v37
	s_cmp_lt_u32 s17, 4
	s_cbranch_scc1 .Lsg_done
	v_fmac_f32_e32 v46, v22, v38
	v_fmac_f32_e32 v47, v22, v39
	s_cmp_lt_u32 s17, 5
	s_cbranch_scc1 .Lsg_done
	v_fmac_f32_e32 v46, v23, v40
	v_fmac_f32_e32 v47, v23, v41
	s_cmp_lt_u32 s17, 6
	s_cbranch_scc1 .Lsg_done
	v_fmac_f32_e32 v46, v24, v42
	v_fmac_f32_e32 v47, v24, v43
	s_cmp_lt_u32 s17, 7
	s_cbranch_scc1 .Lsg_done
	v_fmac_f32_e32 v46, v25, v44
	v_fmac_f32_e32 v47, v25, v45
.Lsg_done:
	v_pk_mul_f32 v[2:3], v[46:47], v[2:3]
	s_nop 0
	v_cvt_pk_bf16_f32 v2, v2, v3
	s_lshl_b32 s36, s21, 12
	s_lshl_b32 s27, s18, 8
	s_add_i32 s36, s36, s27
	s_add_u32 s36, s36, 0x2000800
	s_add_u32 s22, s22, 0x20408000
	s_addc_u32 s23, s23, 0
	s_add_u32 s36, s22, s36
	s_addc_u32 s37, s23, 0
	global_store_dword v28, v2, s[36:37]
	s_branch .LBB0_1092
